# E45: up L0/L1 GEMM epilogues: write-through (sc1) tile stores only on the last tile of the phase, plain stores on earlier tiles (so the next tile's counted vmcnt waits do not sit behind write-through
# baseline (speedup 1.0000x reference)
.LBB0_823:
	v_lshl_add_u32 v150, s36, 8, v3
	v_ashrrev_i32_e32 v151, 31, v150
	v_lshlrev_b64 v[152:153], 13, v[150:151]
	ds_read_b32 v151, v155
	v_max_f32_e32 v124, v124, v124
	v_max_f32_e32 v124, 0, v124
	v_max_f32_e32 v125, v125, v125
	v_max_f32_e32 v126, v126, v126
	s_waitcnt lgkmcnt(0)
	v_mul_f32_e32 v124, v124, v151
	v_max_f32_e32 v125, 0, v125
	v_max_f32_e32 v126, 0, v126
	v_mul_f32_e32 v161, v124, v124
	v_max_f32_e32 v124, v129, v129
	v_mul_f32_e32 v125, v125, v151
	v_mul_f32_e32 v126, v126, v151
	v_lshl_or_b32 v148, s66, 8, v157
	v_max_f32_e32 v128, v128, v128
	v_max_f32_e32 v124, 0, v124
	v_mul_f32_e32 v129, v125, v125
	v_max_f32_e32 v125, v130, v130
	v_mul_f32_e32 v130, v126, v126
	v_max_f32_e32 v126, v131, v131
	v_max_f32_e32 v127, v127, v127
	v_ashrrev_i32_e32 v149, 31, v148
	v_max_f32_e32 v128, 0, v128
	v_mul_f32_e32 v124, v124, v151
	v_max_f32_e32 v125, 0, v125
	v_max_f32_e32 v126, 0, v126
	v_max_f32_e32 v127, 0, v127
	v_max_f32_e32 v116, v116, v116
	v_max_f32_e32 v117, v117, v117
	v_max_f32_e32 v118, v118, v118
	v_lshl_add_u64 v[162:163], s[10:11], 0, v[152:153]
	v_lshlrev_b64 v[152:153], 1, v[148:149]
	v_mul_f32_e32 v128, v128, v151
	v_mul_f32_e32 v124, v124, v124
	v_mul_f32_e32 v125, v125, v151
	v_mul_f32_e32 v126, v126, v151
	v_mul_f32_e32 v127, v127, v151
	v_max_f32_e32 v116, 0, v116
	v_max_f32_e32 v117, 0, v117
	v_max_f32_e32 v118, 0, v118
	v_lshl_add_u64 v[148:149], v[162:163], 0, v[152:153]
	v_mul_f32_e32 v128, v128, v128
	v_mul_f32_e32 v125, v125, v125
	v_mul_f32_e32 v126, v126, v126
	v_mul_f32_e32 v127, v127, v127
	v_cvt_pk_bf16_f32 v124, v128, v124
	v_mul_f32_e32 v116, v116, v151
	v_mul_f32_e32 v117, v117, v151
	v_mul_f32_e32 v118, v118, v151
	v_cvt_pk_bf16_f32 v125, v125, v126
	v_cvt_pk_bf16_f32 v126, v161, v129
	v_cvt_pk_bf16_f32 v127, v130, v127
	s_mov_b32 s101, s0
	s_bitcmp1_b32 s101, 0
	s_cbranch_scc1 .Lwtu0_0_p
	global_store_dwordx4 v[148:149], v[124:127], off sc1
	s_branch .Lwtu0_0_j
.Lwtu0_0_p:
	global_store_dwordx4 v[148:149], v[124:127], off
.Lwtu0_0_j:
	v_max_f32_e32 v120, v120, v120
	v_max_f32_e32 v119, v119, v119
	v_mul_f32_e32 v124, v116, v116
	v_max_f32_e32 v116, v121, v121
	v_mul_f32_e32 v121, v117, v117
	v_max_f32_e32 v117, v122, v122
	v_mul_f32_e32 v122, v118, v118
	v_max_f32_e32 v118, v123, v123
	v_max_f32_e32 v116, 0, v116
	v_max_f32_e32 v117, 0, v117
	v_max_f32_e32 v118, 0, v118
	v_max_f32_e32 v120, 0, v120
	v_mul_f32_e32 v116, v116, v151
	v_mul_f32_e32 v117, v117, v151
	v_mul_f32_e32 v118, v118, v151
	v_max_f32_e32 v119, 0, v119
	v_mul_f32_e32 v120, v120, v151
	v_mul_f32_e32 v116, v116, v116
	v_mul_f32_e32 v117, v117, v117
	v_mul_f32_e32 v119, v119, v151
	v_mul_f32_e32 v118, v118, v118
	v_mul_f32_e32 v120, v120, v120
	v_mul_f32_e32 v119, v119, v119
	v_cvt_pk_bf16_f32 v116, v120, v116
	v_cvt_pk_bf16_f32 v117, v117, v118
	v_cvt_pk_bf16_f32 v118, v124, v121
	v_cvt_pk_bf16_f32 v119, v122, v119
	s_bitcmp1_b32 s101, 0
	s_cbranch_scc1 .Lwtu0_1_p
	global_store_dwordx4 v[148:149], v[116:119], off offset:256 sc1
	s_branch .Lwtu0_1_j
.Lwtu0_1_p:
	global_store_dwordx4 v[148:149], v[116:119], off offset:256
.Lwtu0_1_j:
	ds_read_b32 v118, v155 offset:64
	v_max_f32_e32 v108, v108, v108
	v_max_f32_e32 v108, 0, v108
	v_max_f32_e32 v109, v109, v109
	v_max_f32_e32 v110, v110, v110
	s_waitcnt lgkmcnt(0)
	v_mul_f32_e32 v108, v108, v118
	v_max_f32_e32 v109, 0, v109
	v_max_f32_e32 v110, 0, v110
	v_or_b32_e32 v116, 16, v150
	v_mul_f32_e32 v119, v108, v108
	v_max_f32_e32 v108, v113, v113
	v_mul_f32_e32 v109, v109, v118
	v_mul_f32_e32 v110, v110, v118
	v_ashrrev_i32_e32 v117, 31, v116
	v_max_f32_e32 v112, v112, v112
	v_max_f32_e32 v108, 0, v108
	v_mul_f32_e32 v113, v109, v109
	v_max_f32_e32 v109, v114, v114
	v_mul_f32_e32 v114, v110, v110
	v_max_f32_e32 v110, v115, v115
	v_max_f32_e32 v111, v111, v111
	v_lshlrev_b64 v[116:117], 13, v[116:117]
	v_max_f32_e32 v112, 0, v112
	v_mul_f32_e32 v108, v108, v118
	v_max_f32_e32 v109, 0, v109
	v_max_f32_e32 v110, 0, v110
	v_max_f32_e32 v111, 0, v111
	v_max_f32_e32 v100, v100, v100
	v_max_f32_e32 v101, v101, v101
	v_max_f32_e32 v102, v102, v102
	v_lshl_add_u64 v[116:117], s[10:11], 0, v[116:117]
	v_mul_f32_e32 v112, v112, v118
	v_mul_f32_e32 v108, v108, v108
	v_mul_f32_e32 v109, v109, v118
	v_mul_f32_e32 v110, v110, v118
	v_mul_f32_e32 v111, v111, v118
	v_max_f32_e32 v100, 0, v100
	v_max_f32_e32 v101, 0, v101
	v_max_f32_e32 v102, 0, v102
	v_lshl_add_u64 v[116:117], v[116:117], 0, v[152:153]
	v_mul_f32_e32 v112, v112, v112
	v_mul_f32_e32 v109, v109, v109
	v_mul_f32_e32 v110, v110, v110
	v_mul_f32_e32 v111, v111, v111
	v_cvt_pk_bf16_f32 v108, v112, v108
	v_mul_f32_e32 v100, v100, v118
	v_mul_f32_e32 v101, v101, v118
	v_mul_f32_e32 v102, v102, v118
	v_cvt_pk_bf16_f32 v109, v109, v110
	v_cvt_pk_bf16_f32 v110, v119, v113
	v_cvt_pk_bf16_f32 v111, v114, v111
	s_bitcmp1_b32 s101, 0
	s_cbranch_scc1 .Lwtu0_2_p
	global_store_dwordx4 v[116:117], v[108:111], off sc1
	s_branch .Lwtu0_2_j
.Lwtu0_2_p:
	global_store_dwordx4 v[116:117], v[108:111], off
.Lwtu0_2_j:
	v_max_f32_e32 v104, v104, v104
	v_max_f32_e32 v103, v103, v103
	v_mul_f32_e32 v108, v100, v100
	v_max_f32_e32 v100, v105, v105
	v_mul_f32_e32 v105, v101, v101
	v_max_f32_e32 v101, v106, v106
	v_mul_f32_e32 v106, v102, v102
	v_max_f32_e32 v102, v107, v107
	v_max_f32_e32 v100, 0, v100
	v_max_f32_e32 v101, 0, v101
	v_max_f32_e32 v102, 0, v102
	v_max_f32_e32 v104, 0, v104
	v_mul_f32_e32 v100, v100, v118
	v_mul_f32_e32 v101, v101, v118
	v_mul_f32_e32 v102, v102, v118
	v_max_f32_e32 v103, 0, v103
	v_mul_f32_e32 v104, v104, v118
	v_mul_f32_e32 v100, v100, v100
	v_mul_f32_e32 v101, v101, v101
	v_mul_f32_e32 v103, v103, v118
	v_mul_f32_e32 v102, v102, v102
	v_mul_f32_e32 v104, v104, v104
	v_mul_f32_e32 v103, v103, v103
	v_cvt_pk_bf16_f32 v100, v104, v100
	v_cvt_pk_bf16_f32 v101, v101, v102
	v_cvt_pk_bf16_f32 v102, v108, v105
	v_cvt_pk_bf16_f32 v103, v106, v103
	s_bitcmp1_b32 s101, 0
	s_cbranch_scc1 .Lwtu0_3_p
	global_store_dwordx4 v[116:117], v[100:103], off offset:256 sc1
	s_branch .Lwtu0_3_j
.Lwtu0_3_p:
	global_store_dwordx4 v[116:117], v[100:103], off offset:256
.Lwtu0_3_j:
	ds_read_b32 v102, v155 offset:128
	v_max_f32_e32 v92, v92, v92
	v_max_f32_e32 v92, 0, v92
	v_max_f32_e32 v93, v93, v93
	v_max_f32_e32 v94, v94, v94
	s_waitcnt lgkmcnt(0)
	v_mul_f32_e32 v92, v92, v102
	v_max_f32_e32 v93, 0, v93
	v_max_f32_e32 v94, 0, v94
	v_or_b32_e32 v100, 32, v150
	v_mul_f32_e32 v103, v92, v92
	v_max_f32_e32 v92, v97, v97
	v_mul_f32_e32 v93, v93, v102
	v_mul_f32_e32 v94, v94, v102
	v_ashrrev_i32_e32 v101, 31, v100
	v_max_f32_e32 v96, v96, v96
	v_max_f32_e32 v92, 0, v92
	v_mul_f32_e32 v97, v93, v93
	v_max_f32_e32 v93, v98, v98
	v_mul_f32_e32 v98, v94, v94
	v_max_f32_e32 v94, v99, v99
	v_max_f32_e32 v95, v95, v95
	v_lshlrev_b64 v[100:101], 13, v[100:101]
	v_max_f32_e32 v96, 0, v96
	v_mul_f32_e32 v92, v92, v102
	v_max_f32_e32 v93, 0, v93
	v_max_f32_e32 v94, 0, v94
	v_max_f32_e32 v95, 0, v95
	v_max_f32_e32 v84, v84, v84
	v_max_f32_e32 v85, v85, v85
	v_max_f32_e32 v86, v86, v86
	v_lshl_add_u64 v[100:101], s[10:11], 0, v[100:101]
	v_mul_f32_e32 v96, v96, v102
	v_mul_f32_e32 v92, v92, v92
	v_mul_f32_e32 v93, v93, v102
	v_mul_f32_e32 v94, v94, v102
	v_mul_f32_e32 v95, v95, v102
	v_max_f32_e32 v84, 0, v84
	v_max_f32_e32 v85, 0, v85
	v_max_f32_e32 v86, 0, v86
	v_lshl_add_u64 v[100:101], v[100:101], 0, v[152:153]
	v_mul_f32_e32 v96, v96, v96
	v_mul_f32_e32 v93, v93, v93
	v_mul_f32_e32 v94, v94, v94
	v_mul_f32_e32 v95, v95, v95
	v_cvt_pk_bf16_f32 v92, v96, v92
	v_mul_f32_e32 v84, v84, v102
	v_mul_f32_e32 v85, v85, v102
	v_mul_f32_e32 v86, v86, v102
	v_cvt_pk_bf16_f32 v93, v93, v94
	v_cvt_pk_bf16_f32 v94, v103, v97
	v_cvt_pk_bf16_f32 v95, v98, v95
	s_bitcmp1_b32 s101, 0
	s_cbranch_scc1 .Lwtu0_4_p
	global_store_dwordx4 v[100:101], v[92:95], off sc1
	s_branch .Lwtu0_4_j
.Lwtu0_4_p:
	global_store_dwordx4 v[100:101], v[92:95], off
.Lwtu0_4_j:
	v_max_f32_e32 v88, v88, v88
	v_max_f32_e32 v87, v87, v87
	v_mul_f32_e32 v92, v84, v84
	v_max_f32_e32 v84, v89, v89
	v_mul_f32_e32 v89, v85, v85
	v_max_f32_e32 v85, v90, v90
	v_mul_f32_e32 v90, v86, v86
	v_max_f32_e32 v86, v91, v91
	v_max_f32_e32 v84, 0, v84
	v_max_f32_e32 v85, 0, v85
	v_max_f32_e32 v86, 0, v86
	v_max_f32_e32 v88, 0, v88
	v_mul_f32_e32 v84, v84, v102
	v_mul_f32_e32 v85, v85, v102
	v_mul_f32_e32 v86, v86, v102
	v_max_f32_e32 v87, 0, v87
	v_mul_f32_e32 v88, v88, v102
	v_mul_f32_e32 v84, v84, v84
	v_mul_f32_e32 v85, v85, v85
	v_mul_f32_e32 v87, v87, v102
	v_mul_f32_e32 v86, v86, v86
	v_mul_f32_e32 v88, v88, v88
	v_mul_f32_e32 v87, v87, v87
	v_cvt_pk_bf16_f32 v84, v88, v84
	v_cvt_pk_bf16_f32 v85, v85, v86
	v_cvt_pk_bf16_f32 v86, v92, v89
	v_cvt_pk_bf16_f32 v87, v90, v87
	s_bitcmp1_b32 s101, 0
	s_cbranch_scc1 .Lwtu0_5_p
	global_store_dwordx4 v[100:101], v[84:87], off offset:256 sc1
	s_branch .Lwtu0_5_j
.Lwtu0_5_p:
	global_store_dwordx4 v[100:101], v[84:87], off offset:256
.Lwtu0_5_j:
	ds_read_b32 v86, v155 offset:192
	v_max_f32_e32 v76, v76, v76
	v_max_f32_e32 v76, 0, v76
	v_max_f32_e32 v77, v77, v77
	v_max_f32_e32 v78, v78, v78
	s_waitcnt lgkmcnt(0)
	v_mul_f32_e32 v76, v76, v86
	v_max_f32_e32 v77, 0, v77
	v_max_f32_e32 v78, 0, v78
	v_or_b32_e32 v84, 48, v150
	v_mul_f32_e32 v87, v76, v76
	v_max_f32_e32 v76, v81, v81
	v_mul_f32_e32 v77, v77, v86
	v_mul_f32_e32 v78, v78, v86
	v_ashrrev_i32_e32 v85, 31, v84
	v_max_f32_e32 v80, v80, v80
	v_max_f32_e32 v76, 0, v76
	v_mul_f32_e32 v81, v77, v77
	v_max_f32_e32 v77, v82, v82
	v_mul_f32_e32 v82, v78, v78
	v_max_f32_e32 v78, v83, v83
	v_max_f32_e32 v79, v79, v79
	v_lshlrev_b64 v[84:85], 13, v[84:85]
	v_max_f32_e32 v80, 0, v80
	v_mul_f32_e32 v76, v76, v86
	v_max_f32_e32 v77, 0, v77
	v_max_f32_e32 v78, 0, v78
	v_max_f32_e32 v79, 0, v79
	v_max_f32_e32 v68, v68, v68
	v_max_f32_e32 v69, v69, v69
	v_max_f32_e32 v70, v70, v70
	v_lshl_add_u64 v[84:85], s[10:11], 0, v[84:85]
	v_mul_f32_e32 v80, v80, v86
	v_mul_f32_e32 v76, v76, v76
	v_mul_f32_e32 v77, v77, v86
	v_mul_f32_e32 v78, v78, v86
	v_mul_f32_e32 v79, v79, v86
	v_max_f32_e32 v68, 0, v68
	v_max_f32_e32 v69, 0, v69
	v_max_f32_e32 v70, 0, v70
	v_lshl_add_u64 v[84:85], v[84:85], 0, v[152:153]
	v_mul_f32_e32 v80, v80, v80
	v_mul_f32_e32 v77, v77, v77
	v_mul_f32_e32 v78, v78, v78
	v_mul_f32_e32 v79, v79, v79
	v_cvt_pk_bf16_f32 v76, v80, v76
	v_mul_f32_e32 v68, v68, v86
	v_mul_f32_e32 v69, v69, v86
	v_mul_f32_e32 v70, v70, v86
	v_cvt_pk_bf16_f32 v77, v77, v78
	v_cvt_pk_bf16_f32 v78, v87, v81
	v_cvt_pk_bf16_f32 v79, v82, v79
	s_bitcmp1_b32 s101, 0
	s_cbranch_scc1 .Lwtu0_6_p
	global_store_dwordx4 v[84:85], v[76:79], off sc1
	s_branch .Lwtu0_6_j
.Lwtu0_6_p:
	global_store_dwordx4 v[84:85], v[76:79], off
.Lwtu0_6_j:
	v_max_f32_e32 v72, v72, v72
	v_max_f32_e32 v71, v71, v71
	v_mul_f32_e32 v76, v68, v68
	v_max_f32_e32 v68, v73, v73
	v_mul_f32_e32 v73, v69, v69
	v_max_f32_e32 v69, v74, v74
	v_mul_f32_e32 v74, v70, v70
	v_max_f32_e32 v70, v75, v75
	v_max_f32_e32 v72, 0, v72
	v_max_f32_e32 v68, 0, v68
	v_max_f32_e32 v69, 0, v69
	v_max_f32_e32 v70, 0, v70
	v_max_f32_e32 v71, 0, v71
	v_mul_f32_e32 v72, v72, v86
	v_mul_f32_e32 v68, v68, v86
	v_mul_f32_e32 v69, v69, v86
	v_mul_f32_e32 v70, v70, v86
	v_mul_f32_e32 v71, v71, v86
	v_mul_f32_e32 v72, v72, v72
	v_mul_f32_e32 v68, v68, v68
	v_mul_f32_e32 v69, v69, v69
	v_mul_f32_e32 v70, v70, v70
	v_mul_f32_e32 v71, v71, v71
	v_cvt_pk_bf16_f32 v68, v72, v68
	v_cvt_pk_bf16_f32 v69, v69, v70
	v_cvt_pk_bf16_f32 v70, v76, v73
	v_cvt_pk_bf16_f32 v71, v74, v71
	ds_read_b32 v72, v156
	v_max_f32_e32 v60, v60, v60
	v_max_f32_e32 v60, 0, v60
	v_max_f32_e32 v61, v61, v61
	v_max_f32_e32 v62, v62, v62
	s_waitcnt lgkmcnt(0)
	v_mul_f32_e32 v60, v60, v72
	v_max_f32_e32 v61, 0, v61
	v_max_f32_e32 v62, 0, v62
	s_bitcmp1_b32 s101, 0
	s_cbranch_scc1 .Lwtu0_7_p
	global_store_dwordx4 v[84:85], v[68:71], off offset:256 sc1
	s_branch .Lwtu0_7_j
.Lwtu0_7_p:
	global_store_dwordx4 v[84:85], v[68:71], off offset:256
.Lwtu0_7_j:
	v_max_f32_e32 v64, v64, v64
	v_mul_f32_e32 v61, v61, v72
	v_mul_f32_e32 v70, v60, v60
	v_max_f32_e32 v60, v65, v65
	v_mul_f32_e32 v62, v62, v72
	v_max_f32_e32 v64, 0, v64
	v_max_f32_e32 v60, 0, v60
	v_mul_f32_e32 v65, v61, v61
	v_max_f32_e32 v61, v66, v66
	v_mul_f32_e32 v66, v62, v62
	v_max_f32_e32 v62, v67, v67
	v_mul_f32_e32 v64, v64, v72
	v_mul_f32_e32 v60, v60, v72
	v_max_f32_e32 v61, 0, v61
	v_max_f32_e32 v62, 0, v62
	v_max_f32_e32 v63, v63, v63
	v_mul_f32_e32 v64, v64, v64
	v_mul_f32_e32 v60, v60, v60
	v_mul_f32_e32 v61, v61, v72
	v_mul_f32_e32 v62, v62, v72
	v_max_f32_e32 v63, 0, v63
	v_max_f32_e32 v52, v52, v52
	v_max_f32_e32 v53, v53, v53
	v_max_f32_e32 v54, v54, v54
	v_mul_f32_e32 v61, v61, v61
	v_mul_f32_e32 v63, v63, v72
	v_mul_f32_e32 v62, v62, v62
	v_cvt_pk_bf16_f32 v60, v64, v60
	v_add_co_u32_e32 v64, vcc, s60, v148
	v_max_f32_e32 v52, 0, v52
	v_max_f32_e32 v53, 0, v53
	v_max_f32_e32 v54, 0, v54
	v_mul_f32_e32 v63, v63, v63
	v_cvt_pk_bf16_f32 v61, v61, v62
	v_cvt_pk_bf16_f32 v62, v70, v65
	v_addc_co_u32_e32 v65, vcc, 0, v149, vcc
	v_mul_f32_e32 v52, v52, v72
	v_mul_f32_e32 v53, v53, v72
	v_mul_f32_e32 v54, v54, v72
	v_cvt_pk_bf16_f32 v63, v66, v63
	s_bitcmp1_b32 s101, 0
	s_cbranch_scc1 .Lwtu0_8_p
	global_store_dwordx4 v[64:65], v[60:63], off sc1
	s_branch .Lwtu0_8_j
.Lwtu0_8_p:
	global_store_dwordx4 v[64:65], v[60:63], off
.Lwtu0_8_j:
	v_max_f32_e32 v56, v56, v56
	v_max_f32_e32 v55, v55, v55
	v_mul_f32_e32 v60, v52, v52
	v_max_f32_e32 v52, v57, v57
	v_mul_f32_e32 v57, v53, v53
	v_max_f32_e32 v53, v58, v58
	v_mul_f32_e32 v58, v54, v54
	v_max_f32_e32 v54, v59, v59
	v_max_f32_e32 v56, 0, v56
	v_max_f32_e32 v52, 0, v52
	v_max_f32_e32 v53, 0, v53
	v_max_f32_e32 v54, 0, v54
	v_max_f32_e32 v55, 0, v55
	v_mul_f32_e32 v56, v56, v72
	v_mul_f32_e32 v52, v52, v72
	v_mul_f32_e32 v53, v53, v72
	v_mul_f32_e32 v54, v54, v72
	v_mul_f32_e32 v55, v55, v72
	v_mul_f32_e32 v56, v56, v56
	v_mul_f32_e32 v52, v52, v52
	v_mul_f32_e32 v53, v53, v53
	v_mul_f32_e32 v54, v54, v54
	v_mul_f32_e32 v55, v55, v55
	v_cvt_pk_bf16_f32 v52, v56, v52
	v_cvt_pk_bf16_f32 v53, v53, v54
	v_cvt_pk_bf16_f32 v54, v60, v57
	v_cvt_pk_bf16_f32 v55, v58, v55
	ds_read_b32 v56, v155 offset:576
	v_max_f32_e32 v44, v44, v44
	v_max_f32_e32 v44, 0, v44
	v_max_f32_e32 v45, v45, v45
	v_max_f32_e32 v46, v46, v46
	v_lshl_add_u64 v[68:69], v[148:149], 0, s[18:19]
	s_waitcnt lgkmcnt(0)
	v_mul_f32_e32 v44, v44, v56
	v_max_f32_e32 v45, 0, v45
	v_max_f32_e32 v46, 0, v46
	s_bitcmp1_b32 s101, 0
	s_cbranch_scc1 .Lwtu0_9_p
	global_store_dwordx4 v[68:69], v[52:55], off offset:256 sc1
	s_branch .Lwtu0_9_j
.Lwtu0_9_p:
	global_store_dwordx4 v[68:69], v[52:55], off offset:256
.Lwtu0_9_j:
	v_max_f32_e32 v48, v48, v48
	v_mul_f32_e32 v45, v45, v56
	v_mul_f32_e32 v54, v44, v44
	v_max_f32_e32 v44, v49, v49
	v_mul_f32_e32 v46, v46, v56
	v_max_f32_e32 v48, 0, v48
	v_max_f32_e32 v44, 0, v44
	v_mul_f32_e32 v49, v45, v45
	v_max_f32_e32 v45, v50, v50
	v_mul_f32_e32 v50, v46, v46
	v_max_f32_e32 v46, v51, v51
	v_mul_f32_e32 v48, v48, v56
	v_mul_f32_e32 v44, v44, v56
	v_max_f32_e32 v45, 0, v45
	v_max_f32_e32 v46, 0, v46
	v_max_f32_e32 v47, v47, v47
	v_mul_f32_e32 v48, v48, v48
	v_mul_f32_e32 v44, v44, v44
	v_mul_f32_e32 v45, v45, v56
	v_mul_f32_e32 v46, v46, v56
	v_max_f32_e32 v47, 0, v47
	v_max_f32_e32 v36, v36, v36
	v_max_f32_e32 v37, v37, v37
	v_max_f32_e32 v38, v38, v38
	v_mul_f32_e32 v45, v45, v45
	v_mul_f32_e32 v47, v47, v56
	v_mul_f32_e32 v46, v46, v46
	v_cvt_pk_bf16_f32 v44, v48, v44
	v_add_co_u32_e32 v48, vcc, s61, v148
	v_max_f32_e32 v36, 0, v36
	v_max_f32_e32 v37, 0, v37
	v_max_f32_e32 v38, 0, v38
	v_mul_f32_e32 v47, v47, v47
	v_cvt_pk_bf16_f32 v45, v45, v46
	v_cvt_pk_bf16_f32 v46, v54, v49
	v_addc_co_u32_e32 v49, vcc, 0, v149, vcc
	v_mul_f32_e32 v36, v36, v56
	v_mul_f32_e32 v37, v37, v56
	v_mul_f32_e32 v38, v38, v56
	v_cvt_pk_bf16_f32 v47, v50, v47
	s_bitcmp1_b32 s101, 0
	s_cbranch_scc1 .Lwtu0_10_p
	global_store_dwordx4 v[48:49], v[44:47], off sc1
	s_branch .Lwtu0_10_j
.Lwtu0_10_p:
	global_store_dwordx4 v[48:49], v[44:47], off
.Lwtu0_10_j:
	v_max_f32_e32 v40, v40, v40
	v_max_f32_e32 v39, v39, v39
	v_mul_f32_e32 v44, v36, v36
	v_max_f32_e32 v36, v41, v41
	v_mul_f32_e32 v41, v37, v37
	v_max_f32_e32 v37, v42, v42
	v_mul_f32_e32 v42, v38, v38
	v_max_f32_e32 v38, v43, v43
	v_max_f32_e32 v40, 0, v40
	v_max_f32_e32 v36, 0, v36
	v_max_f32_e32 v37, 0, v37
	v_max_f32_e32 v38, 0, v38
	v_max_f32_e32 v39, 0, v39
	v_mul_f32_e32 v40, v40, v56
	v_mul_f32_e32 v36, v36, v56
	v_mul_f32_e32 v37, v37, v56
	v_mul_f32_e32 v38, v38, v56
	v_mul_f32_e32 v39, v39, v56
	v_mul_f32_e32 v40, v40, v40
	v_mul_f32_e32 v36, v36, v36
	v_mul_f32_e32 v37, v37, v37
	v_mul_f32_e32 v38, v38, v38
	v_mul_f32_e32 v39, v39, v39
	v_cvt_pk_bf16_f32 v36, v40, v36
	v_cvt_pk_bf16_f32 v37, v37, v38
	v_cvt_pk_bf16_f32 v38, v44, v41
	v_cvt_pk_bf16_f32 v39, v42, v39
	ds_read_b32 v40, v155 offset:640
	v_max_f32_e32 v28, v28, v28
	v_max_f32_e32 v28, 0, v28
	v_max_f32_e32 v29, v29, v29
	v_max_f32_e32 v30, v30, v30
	v_lshl_add_u64 v[52:53], v[148:149], 0, s[20:21]
	s_waitcnt lgkmcnt(0)
	v_mul_f32_e32 v28, v28, v40
	v_max_f32_e32 v29, 0, v29
	v_max_f32_e32 v30, 0, v30
	s_bitcmp1_b32 s101, 0
	s_cbranch_scc1 .Lwtu0_11_p
	global_store_dwordx4 v[52:53], v[36:39], off offset:256 sc1
	s_branch .Lwtu0_11_j
.Lwtu0_11_p:
	global_store_dwordx4 v[52:53], v[36:39], off offset:256
.Lwtu0_11_j:
	v_max_f32_e32 v32, v32, v32
	v_mul_f32_e32 v29, v29, v40
	v_mul_f32_e32 v38, v28, v28
	v_max_f32_e32 v28, v33, v33
	v_mul_f32_e32 v30, v30, v40
	v_max_f32_e32 v32, 0, v32
	v_max_f32_e32 v28, 0, v28
	v_mul_f32_e32 v33, v29, v29
	v_max_f32_e32 v29, v34, v34
	v_mul_f32_e32 v34, v30, v30
	v_max_f32_e32 v30, v35, v35
	v_mul_f32_e32 v32, v32, v40
	v_mul_f32_e32 v28, v28, v40
	v_max_f32_e32 v29, 0, v29
	v_max_f32_e32 v30, 0, v30
	v_max_f32_e32 v31, v31, v31
	v_mul_f32_e32 v32, v32, v32
	v_mul_f32_e32 v28, v28, v28
	v_mul_f32_e32 v29, v29, v40
	v_mul_f32_e32 v30, v30, v40
	v_max_f32_e32 v31, 0, v31
	v_max_f32_e32 v20, v20, v20
	v_max_f32_e32 v21, v21, v21
	v_max_f32_e32 v22, v22, v22
	v_mul_f32_e32 v29, v29, v29
	v_mul_f32_e32 v31, v31, v40
	v_mul_f32_e32 v30, v30, v30
	v_cvt_pk_bf16_f32 v28, v32, v28
	v_add_co_u32_e32 v32, vcc, s64, v148
	v_max_f32_e32 v20, 0, v20
	v_max_f32_e32 v21, 0, v21
	v_max_f32_e32 v22, 0, v22
	v_mul_f32_e32 v31, v31, v31
	v_cvt_pk_bf16_f32 v29, v29, v30
	v_cvt_pk_bf16_f32 v30, v38, v33
	v_addc_co_u32_e32 v33, vcc, 0, v149, vcc
	v_mul_f32_e32 v20, v20, v40
	v_mul_f32_e32 v21, v21, v40
	v_mul_f32_e32 v22, v22, v40
	v_cvt_pk_bf16_f32 v31, v34, v31
	s_bitcmp1_b32 s101, 0
	s_cbranch_scc1 .Lwtu0_12_p
	global_store_dwordx4 v[32:33], v[28:31], off sc1
	s_branch .Lwtu0_12_j
.Lwtu0_12_p:
	global_store_dwordx4 v[32:33], v[28:31], off
.Lwtu0_12_j:
	v_max_f32_e32 v24, v24, v24
	v_max_f32_e32 v23, v23, v23
	v_mul_f32_e32 v28, v20, v20
	v_max_f32_e32 v20, v25, v25
	v_mul_f32_e32 v25, v21, v21
	v_max_f32_e32 v21, v26, v26
	v_mul_f32_e32 v26, v22, v22
	v_max_f32_e32 v22, v27, v27
	v_max_f32_e32 v24, 0, v24
	v_max_f32_e32 v20, 0, v20
	v_max_f32_e32 v21, 0, v21
	v_max_f32_e32 v22, 0, v22
	v_max_f32_e32 v23, 0, v23
	v_mul_f32_e32 v24, v24, v40
	v_mul_f32_e32 v20, v20, v40
	v_mul_f32_e32 v21, v21, v40
	v_mul_f32_e32 v22, v22, v40
	v_mul_f32_e32 v23, v23, v40
	v_mul_f32_e32 v24, v24, v24
	v_mul_f32_e32 v20, v20, v20
	v_mul_f32_e32 v21, v21, v21
	v_mul_f32_e32 v22, v22, v22
	v_mul_f32_e32 v23, v23, v23
	v_cvt_pk_bf16_f32 v20, v24, v20
	v_cvt_pk_bf16_f32 v21, v21, v22
	v_cvt_pk_bf16_f32 v22, v28, v25
	v_cvt_pk_bf16_f32 v23, v26, v23
	ds_read_b32 v24, v155 offset:704
	v_max_f32_e32 v12, v12, v12
	v_max_f32_e32 v12, 0, v12
	v_max_f32_e32 v13, v13, v13
	v_max_f32_e32 v14, v14, v14
	v_lshl_add_u64 v[36:37], v[148:149], 0, s[22:23]
	s_waitcnt lgkmcnt(0)
	v_mul_f32_e32 v12, v12, v24
	v_max_f32_e32 v13, 0, v13
	v_max_f32_e32 v14, 0, v14
	s_bitcmp1_b32 s101, 0
	s_cbranch_scc1 .Lwtu0_13_p
	global_store_dwordx4 v[36:37], v[20:23], off offset:256 sc1
	s_branch .Lwtu0_13_j
.Lwtu0_13_p:
	global_store_dwordx4 v[36:37], v[20:23], off offset:256
.Lwtu0_13_j:
	v_max_f32_e32 v16, v16, v16
	v_mul_f32_e32 v13, v13, v24
	v_mul_f32_e32 v22, v12, v12
	v_max_f32_e32 v12, v17, v17
	v_mul_f32_e32 v14, v14, v24
	v_max_f32_e32 v16, 0, v16
	v_max_f32_e32 v12, 0, v12
	v_mul_f32_e32 v17, v13, v13
	v_max_f32_e32 v13, v18, v18
	v_mul_f32_e32 v18, v14, v14
	v_max_f32_e32 v14, v19, v19
	v_mul_f32_e32 v16, v16, v24
	v_mul_f32_e32 v12, v12, v24
	v_max_f32_e32 v13, 0, v13
	v_max_f32_e32 v14, 0, v14
	v_max_f32_e32 v15, v15, v15
	v_mul_f32_e32 v16, v16, v16
	v_mul_f32_e32 v12, v12, v12
	v_mul_f32_e32 v13, v13, v24
	v_mul_f32_e32 v14, v14, v24
	v_max_f32_e32 v15, 0, v15
	v_max_f32_e32 v4, v4, v4
	v_max_f32_e32 v5, v5, v5
	v_max_f32_e32 v6, v6, v6
	v_mul_f32_e32 v13, v13, v13
	v_mul_f32_e32 v15, v15, v24
	v_mul_f32_e32 v14, v14, v14
	v_cvt_pk_bf16_f32 v12, v16, v12
	v_add_co_u32_e32 v16, vcc, s65, v148
	v_max_f32_e32 v4, 0, v4
	v_max_f32_e32 v5, 0, v5
	v_max_f32_e32 v6, 0, v6
	v_mul_f32_e32 v15, v15, v15
	v_cvt_pk_bf16_f32 v13, v13, v14
	v_cvt_pk_bf16_f32 v14, v22, v17
	v_addc_co_u32_e32 v17, vcc, 0, v149, vcc
	v_mul_f32_e32 v4, v4, v24
	v_mul_f32_e32 v5, v5, v24
	v_mul_f32_e32 v6, v6, v24
	v_cvt_pk_bf16_f32 v15, v18, v15
	s_bitcmp1_b32 s101, 0
	s_cbranch_scc1 .Lwtu0_14_p
	global_store_dwordx4 v[16:17], v[12:15], off sc1
	s_branch .Lwtu0_14_j
.Lwtu0_14_p:
	global_store_dwordx4 v[16:17], v[12:15], off
.Lwtu0_14_j:
	v_max_f32_e32 v7, v7, v7
	v_max_f32_e32 v8, v8, v8
	v_mul_f32_e32 v12, v4, v4
	v_max_f32_e32 v4, v9, v9
	v_mul_f32_e32 v9, v5, v5
	v_max_f32_e32 v5, v10, v10
	v_mul_f32_e32 v10, v6, v6
	v_max_f32_e32 v6, v11, v11
	v_max_f32_e32 v4, 0, v4
	v_max_f32_e32 v5, 0, v5
	v_max_f32_e32 v6, 0, v6
	v_max_f32_e32 v7, 0, v7
	v_max_f32_e32 v8, 0, v8
	v_mul_f32_e32 v4, v4, v24
	v_mul_f32_e32 v5, v5, v24
	v_mul_f32_e32 v6, v6, v24
	v_mul_f32_e32 v7, v7, v24
	v_lshl_add_u64 v[20:21], v[148:149], 0, s[24:25]
	v_mul_f32_e32 v8, v8, v24
	v_mul_f32_e32 v4, v4, v4
	v_mul_f32_e32 v5, v5, v5
	v_mul_f32_e32 v6, v6, v6
	v_mul_f32_e32 v7, v7, v7
	s_andn2_b64 vcc, exec, s[0:1]
	s_mov_b64 s[0:1], -1
	v_mul_f32_e32 v8, v8, v8
	v_cvt_pk_bf16_f32 v4, v8, v4
	v_cvt_pk_bf16_f32 v5, v5, v6
	v_cvt_pk_bf16_f32 v6, v12, v9
	v_cvt_pk_bf16_f32 v7, v10, v7
	s_bitcmp1_b32 s101, 0
	s_cbranch_scc1 .Lwtu0_15_p
	global_store_dwordx4 v[20:21], v[4:7], off offset:256 sc1
	s_branch .Lwtu0_15_j
.Lwtu0_15_p:
	global_store_dwordx4 v[20:21], v[4:7], off offset:256
.Lwtu0_15_j:
	s_cbranch_vccnz .LBB0_812
	s_andn2_b64 vcc, exec, s[8:9]
	s_cbranch_vccnz .LBB0_811
	s_barrier
	s_branch .LBB0_811

.LBB0_1756:
	v_lshl_add_u32 v148, s34, 8, v152
	v_ashrrev_i32_e32 v149, 31, v148
	v_lshlrev_b64 v[150:151], 13, v[148:149]
	ds_read_b32 v149, v154
	v_lshl_or_b32 v146, s58, 8, v156
	v_max_f32_e32 v122, v122, v122
	v_ashrrev_i32_e32 v147, 31, v146
	v_max_f32_e32 v122, 0, v122
	v_max_f32_e32 v123, v123, v123
	v_max_f32_e32 v124, v124, v124
	v_lshl_add_u64 v[160:161], s[10:11], 0, v[150:151]
	v_lshlrev_b64 v[150:151], 1, v[146:147]
	s_waitcnt lgkmcnt(0)
	v_mul_f32_e32 v122, v122, v149
	v_max_f32_e32 v123, 0, v123
	v_max_f32_e32 v124, 0, v124
	v_lshl_add_u64 v[146:147], v[160:161], 0, v[150:151]
	v_mul_f32_e32 v160, v122, v122
	v_max_f32_e32 v122, v127, v127
	v_mul_f32_e32 v123, v123, v149
	v_mul_f32_e32 v124, v124, v149
	v_max_f32_e32 v126, v126, v126
	v_max_f32_e32 v122, 0, v122
	v_mul_f32_e32 v127, v123, v123
	v_max_f32_e32 v123, v128, v128
	v_mul_f32_e32 v128, v124, v124
	v_max_f32_e32 v124, v129, v129
	v_max_f32_e32 v125, v125, v125
	v_max_f32_e32 v126, 0, v126
	v_mul_f32_e32 v122, v122, v149
	v_max_f32_e32 v123, 0, v123
	v_max_f32_e32 v124, 0, v124
	v_max_f32_e32 v125, 0, v125
	v_max_f32_e32 v114, v114, v114
	v_max_f32_e32 v115, v115, v115
	v_max_f32_e32 v116, v116, v116
	v_mul_f32_e32 v126, v126, v149
	v_mul_f32_e32 v122, v122, v122
	v_mul_f32_e32 v123, v123, v149
	v_mul_f32_e32 v124, v124, v149
	v_mul_f32_e32 v125, v125, v149
	v_max_f32_e32 v114, 0, v114
	v_max_f32_e32 v115, 0, v115
	v_max_f32_e32 v116, 0, v116
	v_mul_f32_e32 v126, v126, v126
	v_mul_f32_e32 v123, v123, v123
	v_mul_f32_e32 v124, v124, v124
	v_mul_f32_e32 v125, v125, v125
	v_cvt_pk_bf16_f32 v122, v126, v122
	v_mul_f32_e32 v114, v114, v149
	v_mul_f32_e32 v115, v115, v149
	v_mul_f32_e32 v116, v116, v149
	v_cvt_pk_bf16_f32 v123, v123, v124
	v_cvt_pk_bf16_f32 v124, v160, v127
	v_cvt_pk_bf16_f32 v125, v128, v125
	s_mov_b32 s101, s0
	s_bitcmp1_b32 s101, 0
	s_cbranch_scc1 .Lwtu1_0_p
	global_store_dwordx4 v[146:147], v[122:125], off sc1
	s_branch .Lwtu1_0_j
.Lwtu1_0_p:
	global_store_dwordx4 v[146:147], v[122:125], off
.Lwtu1_0_j:
	v_max_f32_e32 v118, v118, v118
	v_max_f32_e32 v117, v117, v117
	v_mul_f32_e32 v122, v114, v114
	v_max_f32_e32 v114, v119, v119
	v_mul_f32_e32 v119, v115, v115
	v_max_f32_e32 v115, v120, v120
	v_mul_f32_e32 v120, v116, v116
	v_max_f32_e32 v116, v121, v121
	v_max_f32_e32 v114, 0, v114
	v_max_f32_e32 v115, 0, v115
	v_max_f32_e32 v116, 0, v116
	v_max_f32_e32 v118, 0, v118
	v_mul_f32_e32 v114, v114, v149
	v_mul_f32_e32 v115, v115, v149
	v_mul_f32_e32 v116, v116, v149
	v_max_f32_e32 v117, 0, v117
	v_mul_f32_e32 v118, v118, v149
	v_mul_f32_e32 v114, v114, v114
	v_mul_f32_e32 v115, v115, v115
	v_mul_f32_e32 v117, v117, v149
	v_mul_f32_e32 v116, v116, v116
	v_mul_f32_e32 v118, v118, v118
	v_mul_f32_e32 v117, v117, v117
	v_cvt_pk_bf16_f32 v114, v118, v114
	v_cvt_pk_bf16_f32 v115, v115, v116
	v_cvt_pk_bf16_f32 v116, v122, v119
	v_cvt_pk_bf16_f32 v117, v120, v117
	s_bitcmp1_b32 s101, 0
	s_cbranch_scc1 .Lwtu1_1_p
	global_store_dwordx4 v[146:147], v[114:117], off offset:256 sc1
	s_branch .Lwtu1_1_j
.Lwtu1_1_p:
	global_store_dwordx4 v[146:147], v[114:117], off offset:256
.Lwtu1_1_j:
	ds_read_b32 v116, v154 offset:64
	v_max_f32_e32 v106, v106, v106
	v_max_f32_e32 v106, 0, v106
	v_max_f32_e32 v107, v107, v107
	v_max_f32_e32 v108, v108, v108
	s_waitcnt lgkmcnt(0)
	v_mul_f32_e32 v106, v106, v116
	v_max_f32_e32 v107, 0, v107
	v_max_f32_e32 v108, 0, v108
	v_or_b32_e32 v114, 16, v148
	v_mul_f32_e32 v117, v106, v106
	v_max_f32_e32 v106, v111, v111
	v_mul_f32_e32 v107, v107, v116
	v_mul_f32_e32 v108, v108, v116
	v_ashrrev_i32_e32 v115, 31, v114
	v_max_f32_e32 v110, v110, v110
	v_max_f32_e32 v106, 0, v106
	v_mul_f32_e32 v111, v107, v107
	v_max_f32_e32 v107, v112, v112
	v_mul_f32_e32 v112, v108, v108
	v_max_f32_e32 v108, v113, v113
	v_max_f32_e32 v109, v109, v109
	v_lshlrev_b64 v[114:115], 13, v[114:115]
	v_max_f32_e32 v110, 0, v110
	v_mul_f32_e32 v106, v106, v116
	v_max_f32_e32 v107, 0, v107
	v_max_f32_e32 v108, 0, v108
	v_max_f32_e32 v109, 0, v109
	v_max_f32_e32 v98, v98, v98
	v_max_f32_e32 v99, v99, v99
	v_max_f32_e32 v100, v100, v100
	v_lshl_add_u64 v[114:115], s[10:11], 0, v[114:115]
	v_mul_f32_e32 v110, v110, v116
	v_mul_f32_e32 v106, v106, v106
	v_mul_f32_e32 v107, v107, v116
	v_mul_f32_e32 v108, v108, v116
	v_mul_f32_e32 v109, v109, v116
	v_max_f32_e32 v98, 0, v98
	v_max_f32_e32 v99, 0, v99
	v_max_f32_e32 v100, 0, v100
	v_lshl_add_u64 v[114:115], v[114:115], 0, v[150:151]
	v_mul_f32_e32 v110, v110, v110
	v_mul_f32_e32 v107, v107, v107
	v_mul_f32_e32 v108, v108, v108
	v_mul_f32_e32 v109, v109, v109
	v_cvt_pk_bf16_f32 v106, v110, v106
	v_mul_f32_e32 v98, v98, v116
	v_mul_f32_e32 v99, v99, v116
	v_mul_f32_e32 v100, v100, v116
	v_cvt_pk_bf16_f32 v107, v107, v108
	v_cvt_pk_bf16_f32 v108, v117, v111
	v_cvt_pk_bf16_f32 v109, v112, v109
	s_bitcmp1_b32 s101, 0
	s_cbranch_scc1 .Lwtu1_2_p
	global_store_dwordx4 v[114:115], v[106:109], off sc1
	s_branch .Lwtu1_2_j
.Lwtu1_2_p:
	global_store_dwordx4 v[114:115], v[106:109], off
.Lwtu1_2_j:
	v_max_f32_e32 v102, v102, v102
	v_max_f32_e32 v101, v101, v101
	v_mul_f32_e32 v106, v98, v98
	v_max_f32_e32 v98, v103, v103
	v_mul_f32_e32 v103, v99, v99
	v_max_f32_e32 v99, v104, v104
	v_mul_f32_e32 v104, v100, v100
	v_max_f32_e32 v100, v105, v105
	v_max_f32_e32 v98, 0, v98
	v_max_f32_e32 v99, 0, v99
	v_max_f32_e32 v100, 0, v100
	v_max_f32_e32 v102, 0, v102
	v_mul_f32_e32 v98, v98, v116
	v_mul_f32_e32 v99, v99, v116
	v_mul_f32_e32 v100, v100, v116
	v_max_f32_e32 v101, 0, v101
	v_mul_f32_e32 v102, v102, v116
	v_mul_f32_e32 v98, v98, v98
	v_mul_f32_e32 v99, v99, v99
	v_mul_f32_e32 v101, v101, v116
	v_mul_f32_e32 v100, v100, v100
	v_mul_f32_e32 v102, v102, v102
	v_mul_f32_e32 v101, v101, v101
	v_cvt_pk_bf16_f32 v98, v102, v98
	v_cvt_pk_bf16_f32 v99, v99, v100
	v_cvt_pk_bf16_f32 v100, v106, v103
	v_cvt_pk_bf16_f32 v101, v104, v101
	s_bitcmp1_b32 s101, 0
	s_cbranch_scc1 .Lwtu1_3_p
	global_store_dwordx4 v[114:115], v[98:101], off offset:256 sc1
	s_branch .Lwtu1_3_j
.Lwtu1_3_p:
	global_store_dwordx4 v[114:115], v[98:101], off offset:256
.Lwtu1_3_j:
	ds_read_b32 v100, v154 offset:128
	v_max_f32_e32 v90, v90, v90
	v_max_f32_e32 v90, 0, v90
	v_max_f32_e32 v91, v91, v91
	v_max_f32_e32 v92, v92, v92
	s_waitcnt lgkmcnt(0)
	v_mul_f32_e32 v90, v90, v100
	v_max_f32_e32 v91, 0, v91
	v_max_f32_e32 v92, 0, v92
	v_or_b32_e32 v98, 32, v148
	v_mul_f32_e32 v101, v90, v90
	v_max_f32_e32 v90, v95, v95
	v_mul_f32_e32 v91, v91, v100
	v_mul_f32_e32 v92, v92, v100
	v_ashrrev_i32_e32 v99, 31, v98
	v_max_f32_e32 v94, v94, v94
	v_max_f32_e32 v90, 0, v90
	v_mul_f32_e32 v95, v91, v91
	v_max_f32_e32 v91, v96, v96
	v_mul_f32_e32 v96, v92, v92
	v_max_f32_e32 v92, v97, v97
	v_max_f32_e32 v93, v93, v93
	v_lshlrev_b64 v[98:99], 13, v[98:99]
	v_max_f32_e32 v94, 0, v94
	v_mul_f32_e32 v90, v90, v100
	v_max_f32_e32 v91, 0, v91
	v_max_f32_e32 v92, 0, v92
	v_max_f32_e32 v93, 0, v93
	v_max_f32_e32 v82, v82, v82
	v_max_f32_e32 v83, v83, v83
	v_max_f32_e32 v84, v84, v84
	v_lshl_add_u64 v[98:99], s[10:11], 0, v[98:99]
	v_mul_f32_e32 v94, v94, v100
	v_mul_f32_e32 v90, v90, v90
	v_mul_f32_e32 v91, v91, v100
	v_mul_f32_e32 v92, v92, v100
	v_mul_f32_e32 v93, v93, v100
	v_max_f32_e32 v82, 0, v82
	v_max_f32_e32 v83, 0, v83
	v_max_f32_e32 v84, 0, v84
	v_lshl_add_u64 v[98:99], v[98:99], 0, v[150:151]
	v_mul_f32_e32 v94, v94, v94
	v_mul_f32_e32 v91, v91, v91
	v_mul_f32_e32 v92, v92, v92
	v_mul_f32_e32 v93, v93, v93
	v_cvt_pk_bf16_f32 v90, v94, v90
	v_mul_f32_e32 v82, v82, v100
	v_mul_f32_e32 v83, v83, v100
	v_mul_f32_e32 v84, v84, v100
	v_cvt_pk_bf16_f32 v91, v91, v92
	v_cvt_pk_bf16_f32 v92, v101, v95
	v_cvt_pk_bf16_f32 v93, v96, v93
	s_bitcmp1_b32 s101, 0
	s_cbranch_scc1 .Lwtu1_4_p
	global_store_dwordx4 v[98:99], v[90:93], off sc1
	s_branch .Lwtu1_4_j
.Lwtu1_4_p:
	global_store_dwordx4 v[98:99], v[90:93], off
.Lwtu1_4_j:
	v_max_f32_e32 v86, v86, v86
	v_max_f32_e32 v85, v85, v85
	v_mul_f32_e32 v90, v82, v82
	v_max_f32_e32 v82, v87, v87
	v_mul_f32_e32 v87, v83, v83
	v_max_f32_e32 v83, v88, v88
	v_mul_f32_e32 v88, v84, v84
	v_max_f32_e32 v84, v89, v89
	v_max_f32_e32 v82, 0, v82
	v_max_f32_e32 v83, 0, v83
	v_max_f32_e32 v84, 0, v84
	v_max_f32_e32 v86, 0, v86
	v_mul_f32_e32 v82, v82, v100
	v_mul_f32_e32 v83, v83, v100
	v_mul_f32_e32 v84, v84, v100
	v_max_f32_e32 v85, 0, v85
	v_mul_f32_e32 v86, v86, v100
	v_mul_f32_e32 v82, v82, v82
	v_mul_f32_e32 v83, v83, v83
	v_mul_f32_e32 v85, v85, v100
	v_mul_f32_e32 v84, v84, v84
	v_mul_f32_e32 v86, v86, v86
	v_mul_f32_e32 v85, v85, v85
	v_cvt_pk_bf16_f32 v82, v86, v82
	v_cvt_pk_bf16_f32 v83, v83, v84
	v_cvt_pk_bf16_f32 v84, v90, v87
	v_cvt_pk_bf16_f32 v85, v88, v85
	s_bitcmp1_b32 s101, 0
	s_cbranch_scc1 .Lwtu1_5_p
	global_store_dwordx4 v[98:99], v[82:85], off offset:256 sc1
	s_branch .Lwtu1_5_j
.Lwtu1_5_p:
	global_store_dwordx4 v[98:99], v[82:85], off offset:256
.Lwtu1_5_j:
	ds_read_b32 v84, v154 offset:192
	v_max_f32_e32 v74, v74, v74
	v_max_f32_e32 v74, 0, v74
	v_max_f32_e32 v75, v75, v75
	v_max_f32_e32 v76, v76, v76
	s_waitcnt lgkmcnt(0)
	v_mul_f32_e32 v74, v74, v84
	v_max_f32_e32 v75, 0, v75
	v_max_f32_e32 v76, 0, v76
	v_or_b32_e32 v82, 48, v148
	v_mul_f32_e32 v85, v74, v74
	v_max_f32_e32 v74, v79, v79
	v_mul_f32_e32 v75, v75, v84
	v_mul_f32_e32 v76, v76, v84
	v_ashrrev_i32_e32 v83, 31, v82
	v_max_f32_e32 v78, v78, v78
	v_max_f32_e32 v74, 0, v74
	v_mul_f32_e32 v79, v75, v75
	v_max_f32_e32 v75, v80, v80
	v_mul_f32_e32 v80, v76, v76
	v_max_f32_e32 v76, v81, v81
	v_max_f32_e32 v77, v77, v77
	v_lshlrev_b64 v[82:83], 13, v[82:83]
	v_max_f32_e32 v78, 0, v78
	v_mul_f32_e32 v74, v74, v84
	v_max_f32_e32 v75, 0, v75
	v_max_f32_e32 v76, 0, v76
	v_max_f32_e32 v77, 0, v77
	v_max_f32_e32 v66, v66, v66
	v_max_f32_e32 v67, v67, v67
	v_max_f32_e32 v68, v68, v68
	v_lshl_add_u64 v[82:83], s[10:11], 0, v[82:83]
	v_mul_f32_e32 v78, v78, v84
	v_mul_f32_e32 v74, v74, v74
	v_mul_f32_e32 v75, v75, v84
	v_mul_f32_e32 v76, v76, v84
	v_mul_f32_e32 v77, v77, v84
	v_max_f32_e32 v66, 0, v66
	v_max_f32_e32 v67, 0, v67
	v_max_f32_e32 v68, 0, v68
	v_lshl_add_u64 v[82:83], v[82:83], 0, v[150:151]
	v_mul_f32_e32 v78, v78, v78
	v_mul_f32_e32 v75, v75, v75
	v_mul_f32_e32 v76, v76, v76
	v_mul_f32_e32 v77, v77, v77
	v_cvt_pk_bf16_f32 v74, v78, v74
	v_mul_f32_e32 v66, v66, v84
	v_mul_f32_e32 v67, v67, v84
	v_mul_f32_e32 v68, v68, v84
	v_cvt_pk_bf16_f32 v75, v75, v76
	v_cvt_pk_bf16_f32 v76, v85, v79
	v_cvt_pk_bf16_f32 v77, v80, v77
	s_bitcmp1_b32 s101, 0
	s_cbranch_scc1 .Lwtu1_6_p
	global_store_dwordx4 v[82:83], v[74:77], off sc1
	s_branch .Lwtu1_6_j
.Lwtu1_6_p:
	global_store_dwordx4 v[82:83], v[74:77], off
.Lwtu1_6_j:
	v_max_f32_e32 v70, v70, v70
	v_max_f32_e32 v69, v69, v69
	v_mul_f32_e32 v74, v66, v66
	v_max_f32_e32 v66, v71, v71
	v_mul_f32_e32 v71, v67, v67
	v_max_f32_e32 v67, v72, v72
	v_mul_f32_e32 v72, v68, v68
	v_max_f32_e32 v68, v73, v73
	v_max_f32_e32 v70, 0, v70
	v_max_f32_e32 v66, 0, v66
	v_max_f32_e32 v67, 0, v67
	v_max_f32_e32 v68, 0, v68
	v_max_f32_e32 v69, 0, v69
	v_mul_f32_e32 v70, v70, v84
	v_mul_f32_e32 v66, v66, v84
	v_mul_f32_e32 v67, v67, v84
	v_mul_f32_e32 v68, v68, v84
	v_mul_f32_e32 v69, v69, v84
	v_mul_f32_e32 v70, v70, v70
	v_mul_f32_e32 v66, v66, v66
	v_mul_f32_e32 v67, v67, v67
	v_mul_f32_e32 v68, v68, v68
	v_mul_f32_e32 v69, v69, v69
	v_cvt_pk_bf16_f32 v66, v70, v66
	v_cvt_pk_bf16_f32 v67, v67, v68
	v_cvt_pk_bf16_f32 v68, v74, v71
	v_cvt_pk_bf16_f32 v69, v72, v69
	ds_read_b32 v70, v155
	v_max_f32_e32 v58, v58, v58
	v_max_f32_e32 v58, 0, v58
	v_max_f32_e32 v59, v59, v59
	v_max_f32_e32 v60, v60, v60
	s_waitcnt lgkmcnt(0)
	v_mul_f32_e32 v58, v58, v70
	v_max_f32_e32 v59, 0, v59
	v_max_f32_e32 v60, 0, v60
	s_bitcmp1_b32 s101, 0
	s_cbranch_scc1 .Lwtu1_7_p
	global_store_dwordx4 v[82:83], v[66:69], off offset:256 sc1
	s_branch .Lwtu1_7_j
.Lwtu1_7_p:
	global_store_dwordx4 v[82:83], v[66:69], off offset:256
.Lwtu1_7_j:
	v_max_f32_e32 v62, v62, v62
	v_mul_f32_e32 v59, v59, v70
	v_mul_f32_e32 v68, v58, v58
	v_max_f32_e32 v58, v63, v63
	v_mul_f32_e32 v60, v60, v70
	v_max_f32_e32 v62, 0, v62
	v_max_f32_e32 v58, 0, v58
	v_mul_f32_e32 v63, v59, v59
	v_max_f32_e32 v59, v64, v64
	v_mul_f32_e32 v64, v60, v60
	v_max_f32_e32 v60, v65, v65
	v_mul_f32_e32 v62, v62, v70
	v_mul_f32_e32 v58, v58, v70
	v_max_f32_e32 v59, 0, v59
	v_max_f32_e32 v60, 0, v60
	v_max_f32_e32 v61, v61, v61
	v_mul_f32_e32 v62, v62, v62
	v_mul_f32_e32 v58, v58, v58
	v_mul_f32_e32 v59, v59, v70
	v_mul_f32_e32 v60, v60, v70
	v_max_f32_e32 v61, 0, v61
	v_max_f32_e32 v50, v50, v50
	v_max_f32_e32 v51, v51, v51
	v_max_f32_e32 v52, v52, v52
	v_mul_f32_e32 v59, v59, v59
	v_mul_f32_e32 v61, v61, v70
	v_mul_f32_e32 v60, v60, v60
	v_cvt_pk_bf16_f32 v58, v62, v58
	v_add_co_u32_e32 v62, vcc, s52, v146
	v_max_f32_e32 v50, 0, v50
	v_max_f32_e32 v51, 0, v51
	v_max_f32_e32 v52, 0, v52
	v_mul_f32_e32 v61, v61, v61
	v_cvt_pk_bf16_f32 v59, v59, v60
	v_cvt_pk_bf16_f32 v60, v68, v63
	v_addc_co_u32_e32 v63, vcc, 0, v147, vcc
	v_mul_f32_e32 v50, v50, v70
	v_mul_f32_e32 v51, v51, v70
	v_mul_f32_e32 v52, v52, v70
	v_cvt_pk_bf16_f32 v61, v64, v61
	s_bitcmp1_b32 s101, 0
	s_cbranch_scc1 .Lwtu1_8_p
	global_store_dwordx4 v[62:63], v[58:61], off sc1
	s_branch .Lwtu1_8_j
.Lwtu1_8_p:
	global_store_dwordx4 v[62:63], v[58:61], off
.Lwtu1_8_j:
	v_max_f32_e32 v54, v54, v54
	v_max_f32_e32 v53, v53, v53
	v_mul_f32_e32 v58, v50, v50
	v_max_f32_e32 v50, v55, v55
	v_mul_f32_e32 v55, v51, v51
	v_max_f32_e32 v51, v56, v56
	v_mul_f32_e32 v56, v52, v52
	v_max_f32_e32 v52, v57, v57
	v_max_f32_e32 v54, 0, v54
	v_max_f32_e32 v50, 0, v50
	v_max_f32_e32 v51, 0, v51
	v_max_f32_e32 v52, 0, v52
	v_max_f32_e32 v53, 0, v53
	v_mul_f32_e32 v54, v54, v70
	v_mul_f32_e32 v50, v50, v70
	v_mul_f32_e32 v51, v51, v70
	v_mul_f32_e32 v52, v52, v70
	v_mul_f32_e32 v53, v53, v70
	v_mul_f32_e32 v54, v54, v54
	v_mul_f32_e32 v50, v50, v50
	v_mul_f32_e32 v51, v51, v51
	v_mul_f32_e32 v52, v52, v52
	v_mul_f32_e32 v53, v53, v53
	v_cvt_pk_bf16_f32 v50, v54, v50
	v_cvt_pk_bf16_f32 v51, v51, v52
	v_cvt_pk_bf16_f32 v52, v58, v55
	v_cvt_pk_bf16_f32 v53, v56, v53
	ds_read_b32 v54, v154 offset:576
	v_max_f32_e32 v42, v42, v42
	v_max_f32_e32 v42, 0, v42
	v_max_f32_e32 v43, v43, v43
	v_max_f32_e32 v44, v44, v44
	v_lshl_add_u64 v[66:67], v[146:147], 0, s[16:17]
	s_waitcnt lgkmcnt(0)
	v_mul_f32_e32 v42, v42, v54
	v_max_f32_e32 v43, 0, v43
	v_max_f32_e32 v44, 0, v44
	s_bitcmp1_b32 s101, 0
	s_cbranch_scc1 .Lwtu1_9_p
	global_store_dwordx4 v[66:67], v[50:53], off offset:256 sc1
	s_branch .Lwtu1_9_j
.Lwtu1_9_p:
	global_store_dwordx4 v[66:67], v[50:53], off offset:256
.Lwtu1_9_j:
	v_max_f32_e32 v46, v46, v46
	v_mul_f32_e32 v43, v43, v54
	v_mul_f32_e32 v52, v42, v42
	v_max_f32_e32 v42, v47, v47
	v_mul_f32_e32 v44, v44, v54
	v_max_f32_e32 v46, 0, v46
	v_max_f32_e32 v42, 0, v42
	v_mul_f32_e32 v47, v43, v43
	v_max_f32_e32 v43, v48, v48
	v_mul_f32_e32 v48, v44, v44
	v_max_f32_e32 v44, v49, v49
	v_mul_f32_e32 v46, v46, v54
	v_mul_f32_e32 v42, v42, v54
	v_max_f32_e32 v43, 0, v43
	v_max_f32_e32 v44, 0, v44
	v_max_f32_e32 v45, v45, v45
	v_mul_f32_e32 v46, v46, v46
	v_mul_f32_e32 v42, v42, v42
	v_mul_f32_e32 v43, v43, v54
	v_mul_f32_e32 v44, v44, v54
	v_max_f32_e32 v45, 0, v45
	v_max_f32_e32 v34, v34, v34
	v_max_f32_e32 v35, v35, v35
	v_max_f32_e32 v36, v36, v36
	v_mul_f32_e32 v43, v43, v43
	v_mul_f32_e32 v45, v45, v54
	v_mul_f32_e32 v44, v44, v44
	v_cvt_pk_bf16_f32 v42, v46, v42
	v_add_co_u32_e32 v46, vcc, s53, v146
	v_max_f32_e32 v34, 0, v34
	v_max_f32_e32 v35, 0, v35
	v_max_f32_e32 v36, 0, v36
	v_mul_f32_e32 v45, v45, v45
	v_cvt_pk_bf16_f32 v43, v43, v44
	v_cvt_pk_bf16_f32 v44, v52, v47
	v_addc_co_u32_e32 v47, vcc, 0, v147, vcc
	v_mul_f32_e32 v34, v34, v54
	v_mul_f32_e32 v35, v35, v54
	v_mul_f32_e32 v36, v36, v54
	v_cvt_pk_bf16_f32 v45, v48, v45
	s_bitcmp1_b32 s101, 0
	s_cbranch_scc1 .Lwtu1_10_p
	global_store_dwordx4 v[46:47], v[42:45], off sc1
	s_branch .Lwtu1_10_j
.Lwtu1_10_p:
	global_store_dwordx4 v[46:47], v[42:45], off
.Lwtu1_10_j:
	v_max_f32_e32 v38, v38, v38
	v_max_f32_e32 v37, v37, v37
	v_mul_f32_e32 v42, v34, v34
	v_max_f32_e32 v34, v39, v39
	v_mul_f32_e32 v39, v35, v35
	v_max_f32_e32 v35, v40, v40
	v_mul_f32_e32 v40, v36, v36
	v_max_f32_e32 v36, v41, v41
	v_max_f32_e32 v38, 0, v38
	v_max_f32_e32 v34, 0, v34
	v_max_f32_e32 v35, 0, v35
	v_max_f32_e32 v36, 0, v36
	v_max_f32_e32 v37, 0, v37
	v_mul_f32_e32 v38, v38, v54
	v_mul_f32_e32 v34, v34, v54
	v_mul_f32_e32 v35, v35, v54
	v_mul_f32_e32 v36, v36, v54
	v_mul_f32_e32 v37, v37, v54
	v_mul_f32_e32 v38, v38, v38
	v_mul_f32_e32 v34, v34, v34
	v_mul_f32_e32 v35, v35, v35
	v_mul_f32_e32 v36, v36, v36
	v_mul_f32_e32 v37, v37, v37
	v_cvt_pk_bf16_f32 v34, v38, v34
	v_cvt_pk_bf16_f32 v35, v35, v36
	v_cvt_pk_bf16_f32 v36, v42, v39
	v_cvt_pk_bf16_f32 v37, v40, v37
	ds_read_b32 v38, v154 offset:640
	v_max_f32_e32 v26, v26, v26
	v_max_f32_e32 v26, 0, v26
	v_max_f32_e32 v27, v27, v27
	v_max_f32_e32 v28, v28, v28
	v_lshl_add_u64 v[50:51], v[146:147], 0, s[18:19]
	s_waitcnt lgkmcnt(0)
	v_mul_f32_e32 v26, v26, v38
	v_max_f32_e32 v27, 0, v27
	v_max_f32_e32 v28, 0, v28
	s_bitcmp1_b32 s101, 0
	s_cbranch_scc1 .Lwtu1_11_p
	global_store_dwordx4 v[50:51], v[34:37], off offset:256 sc1
	s_branch .Lwtu1_11_j
.Lwtu1_11_p:
	global_store_dwordx4 v[50:51], v[34:37], off offset:256
.Lwtu1_11_j:
	v_max_f32_e32 v30, v30, v30
	v_mul_f32_e32 v27, v27, v38
	v_mul_f32_e32 v36, v26, v26
	v_max_f32_e32 v26, v31, v31
	v_mul_f32_e32 v28, v28, v38
	v_max_f32_e32 v30, 0, v30
	v_max_f32_e32 v26, 0, v26
	v_mul_f32_e32 v31, v27, v27
	v_max_f32_e32 v27, v32, v32
	v_mul_f32_e32 v32, v28, v28
	v_max_f32_e32 v28, v33, v33
	v_mul_f32_e32 v30, v30, v38
	v_mul_f32_e32 v26, v26, v38
	v_max_f32_e32 v27, 0, v27
	v_max_f32_e32 v28, 0, v28
	v_max_f32_e32 v29, v29, v29
	v_mul_f32_e32 v30, v30, v30
	v_mul_f32_e32 v26, v26, v26
	v_mul_f32_e32 v27, v27, v38
	v_mul_f32_e32 v28, v28, v38
	v_max_f32_e32 v29, 0, v29
	v_max_f32_e32 v18, v18, v18
	v_max_f32_e32 v19, v19, v19
	v_max_f32_e32 v20, v20, v20
	v_mul_f32_e32 v27, v27, v27
	v_mul_f32_e32 v29, v29, v38
	v_mul_f32_e32 v28, v28, v28
	v_cvt_pk_bf16_f32 v26, v30, v26
	v_add_co_u32_e32 v30, vcc, s54, v146
	v_max_f32_e32 v18, 0, v18
	v_max_f32_e32 v19, 0, v19
	v_max_f32_e32 v20, 0, v20
	v_mul_f32_e32 v29, v29, v29
	v_cvt_pk_bf16_f32 v27, v27, v28
	v_cvt_pk_bf16_f32 v28, v36, v31
	v_addc_co_u32_e32 v31, vcc, 0, v147, vcc
	v_mul_f32_e32 v18, v18, v38
	v_mul_f32_e32 v19, v19, v38
	v_mul_f32_e32 v20, v20, v38
	v_cvt_pk_bf16_f32 v29, v32, v29
	s_bitcmp1_b32 s101, 0
	s_cbranch_scc1 .Lwtu1_12_p
	global_store_dwordx4 v[30:31], v[26:29], off sc1
	s_branch .Lwtu1_12_j
.Lwtu1_12_p:
	global_store_dwordx4 v[30:31], v[26:29], off
.Lwtu1_12_j:
	v_max_f32_e32 v22, v22, v22
	v_max_f32_e32 v21, v21, v21
	v_mul_f32_e32 v26, v18, v18
	v_max_f32_e32 v18, v23, v23
	v_mul_f32_e32 v23, v19, v19
	v_max_f32_e32 v19, v24, v24
	v_mul_f32_e32 v24, v20, v20
	v_max_f32_e32 v20, v25, v25
	v_max_f32_e32 v22, 0, v22
	v_max_f32_e32 v18, 0, v18
	v_max_f32_e32 v19, 0, v19
	v_max_f32_e32 v20, 0, v20
	v_max_f32_e32 v21, 0, v21
	v_mul_f32_e32 v22, v22, v38
	v_mul_f32_e32 v18, v18, v38
	v_mul_f32_e32 v19, v19, v38
	v_mul_f32_e32 v20, v20, v38
	v_mul_f32_e32 v21, v21, v38
	v_mul_f32_e32 v22, v22, v22
	v_mul_f32_e32 v18, v18, v18
	v_mul_f32_e32 v19, v19, v19
	v_mul_f32_e32 v20, v20, v20
	v_mul_f32_e32 v21, v21, v21
	v_cvt_pk_bf16_f32 v18, v22, v18
	v_cvt_pk_bf16_f32 v19, v19, v20
	v_cvt_pk_bf16_f32 v20, v26, v23
	v_cvt_pk_bf16_f32 v21, v24, v21
	ds_read_b32 v22, v154 offset:704
	v_max_f32_e32 v10, v10, v10
	v_max_f32_e32 v10, 0, v10
	v_max_f32_e32 v11, v11, v11
	v_max_f32_e32 v12, v12, v12
	v_lshl_add_u64 v[34:35], v[146:147], 0, s[20:21]
	s_waitcnt lgkmcnt(0)
	v_mul_f32_e32 v10, v10, v22
	v_max_f32_e32 v11, 0, v11
	v_max_f32_e32 v12, 0, v12
	s_bitcmp1_b32 s101, 0
	s_cbranch_scc1 .Lwtu1_13_p
	global_store_dwordx4 v[34:35], v[18:21], off offset:256 sc1
	s_branch .Lwtu1_13_j
.Lwtu1_13_p:
	global_store_dwordx4 v[34:35], v[18:21], off offset:256
.Lwtu1_13_j:
	v_max_f32_e32 v14, v14, v14
	v_mul_f32_e32 v11, v11, v22
	v_mul_f32_e32 v20, v10, v10
	v_max_f32_e32 v10, v15, v15
	v_mul_f32_e32 v12, v12, v22
	v_max_f32_e32 v14, 0, v14
	v_max_f32_e32 v10, 0, v10
	v_mul_f32_e32 v15, v11, v11
	v_max_f32_e32 v11, v16, v16
	v_mul_f32_e32 v16, v12, v12
	v_max_f32_e32 v12, v17, v17
	v_mul_f32_e32 v14, v14, v22
	v_mul_f32_e32 v10, v10, v22
	v_max_f32_e32 v11, 0, v11
	v_max_f32_e32 v12, 0, v12
	v_max_f32_e32 v13, v13, v13
	v_mul_f32_e32 v14, v14, v14
	v_mul_f32_e32 v10, v10, v10
	v_mul_f32_e32 v11, v11, v22
	v_mul_f32_e32 v12, v12, v22
	v_max_f32_e32 v13, 0, v13
	v_max_f32_e32 v2, v2, v2
	v_max_f32_e32 v3, v3, v3
	v_max_f32_e32 v4, v4, v4
	v_mul_f32_e32 v11, v11, v11
	v_mul_f32_e32 v13, v13, v22
	v_mul_f32_e32 v12, v12, v12
	v_cvt_pk_bf16_f32 v10, v14, v10
	v_add_co_u32_e32 v14, vcc, s55, v146
	v_max_f32_e32 v2, 0, v2
	v_max_f32_e32 v3, 0, v3
	v_max_f32_e32 v4, 0, v4
	v_mul_f32_e32 v13, v13, v13
	v_cvt_pk_bf16_f32 v11, v11, v12
	v_cvt_pk_bf16_f32 v12, v20, v15
	v_addc_co_u32_e32 v15, vcc, 0, v147, vcc
	v_mul_f32_e32 v2, v2, v22
	v_mul_f32_e32 v3, v3, v22
	v_mul_f32_e32 v4, v4, v22
	v_cvt_pk_bf16_f32 v13, v16, v13
	s_bitcmp1_b32 s101, 0
	s_cbranch_scc1 .Lwtu1_14_p
	global_store_dwordx4 v[14:15], v[10:13], off sc1
	s_branch .Lwtu1_14_j
.Lwtu1_14_p:
	global_store_dwordx4 v[14:15], v[10:13], off
.Lwtu1_14_j:
	v_max_f32_e32 v5, v5, v5
	v_max_f32_e32 v6, v6, v6
	v_mul_f32_e32 v10, v2, v2
	v_max_f32_e32 v2, v7, v7
	v_mul_f32_e32 v7, v3, v3
	v_max_f32_e32 v3, v8, v8
	v_mul_f32_e32 v8, v4, v4
	v_max_f32_e32 v4, v9, v9
	v_max_f32_e32 v2, 0, v2
	v_max_f32_e32 v3, 0, v3
	v_max_f32_e32 v4, 0, v4
	v_max_f32_e32 v5, 0, v5
	v_max_f32_e32 v6, 0, v6
	v_mul_f32_e32 v2, v2, v22
	v_mul_f32_e32 v3, v3, v22
	v_mul_f32_e32 v4, v4, v22
	v_mul_f32_e32 v5, v5, v22
	v_lshl_add_u64 v[18:19], v[146:147], 0, s[22:23]
	v_mul_f32_e32 v6, v6, v22
	v_mul_f32_e32 v2, v2, v2
	v_mul_f32_e32 v3, v3, v3
	v_mul_f32_e32 v4, v4, v4
	v_mul_f32_e32 v5, v5, v5
	s_andn2_b64 vcc, exec, s[0:1]
	s_mov_b64 s[0:1], -1
	v_mul_f32_e32 v6, v6, v6
	v_cvt_pk_bf16_f32 v2, v6, v2
	v_cvt_pk_bf16_f32 v3, v3, v4
	v_cvt_pk_bf16_f32 v4, v10, v7
	v_cvt_pk_bf16_f32 v5, v8, v5
	s_bitcmp1_b32 s101, 0
	s_cbranch_scc1 .Lwtu1_15_p
	global_store_dwordx4 v[18:19], v[2:5], off offset:256 sc1
	s_branch .Lwtu1_15_j
.Lwtu1_15_p:
	global_store_dwordx4 v[18:19], v[2:5], off offset:256
